# PN gate reduction: 48 ds_bpermute butterfly replaced by permlane32/16 swap transpose-reduce + in-row DPP adds, 4 row-leader lanes store 2 gates each
# speedup vs baseline: 1.0152x; 1.0041x over previous
; DI void phase_norm(const Params& p, int l, const float* xin, LAS unsigned char* lds, int G, int bid) {
;     ...
;     f32x4 w0[4][4], w1[4][4];
; #pragma unroll
;     for (int j = 0; j < 4; ++j)
; #pragma unroll
;         for (int e = 0; e < 4; ++e) { const int k = 256 * j + 4 * lane + e; w0[j][e] = *(const f32x4*)(wg + (size_t)k * 8); w1[j][e] = *(const f32x4*)(wg + (size_t)k * 8 + 4); }
;     f32x4 vn[4];
;     if (gw < M) {
; #pragma unroll
;         for (int j = 0; j < 4; ++j) vn[j] = ((const f32x4*)(xin + (size_t)gw * D) + lane)[64 * j]; }
;     for (int row = gw; row < M; row += NGW) {
;     ...
; #pragma unroll
;         for (int e = 0; e < 4; ++e) { g0[e] = wave_sum(g0[e]); g1[e] = wave_sum(g1[e]); }
;         if (lane == 0) { *(f32x4*)(gates + (size_t)row * 8) = g0; *(f32x4*)(gates + (size_t)row * 8 + 4) = g1; }
.LBB0_137:
	s_or_b64 exec, exec, s[18:19]
	v_ashrrev_i32_e32 v42, 6, v2
	v_readlane_b32 s0, v250, 2
	s_lshl_b64 s[18:19], s[26:27], 15
	v_readlane_b32 s1, v250, 3
	v_add_u32_e32 v178, s0, v42
	s_mov_b32 s0, 0x8000
	v_cmp_gt_i32_e32 vcc, s0, v178
	s_waitcnt lgkmcnt(0)
	s_barrier
	s_and_saveexec_b64 s[46:47], vcc
	s_cbranch_execz .LBB0_144
	v_readlane_b32 s0, v252, 14
	s_add_u32 s0, s0, s18
	v_readlane_b32 s1, v252, 15
	v_and_b32_e32 v43, 63, v2
	s_addc_u32 s1, s1, s19
	v_lshlrev_b32_e32 v0, 7, v43
	v_lshl_add_u64 v[44:45], s[0:1], 0, v[0:1]
	v_add_co_u32_e32 v34, vcc, s89, v44
	s_movk_i32 s6, 0x4000
	s_nop 0
	v_addc_co_u32_e32 v35, vcc, 0, v45, vcc
	s_mov_b64 s[8:9], 0x2040
	v_add_co_u32_e32 v50, vcc, s6, v44
	v_lshl_add_u64 v[46:47], v[44:45], 0, s[8:9]
	s_mov_b64 s[8:9], 0x4040
	v_addc_co_u32_e32 v51, vcc, 0, v45, vcc
	s_movk_i32 s6, 0x6000
	v_lshl_add_u64 v[62:63], v[44:45], 0, s[8:9]
	s_mov_b64 s[8:9], 0x6040
	v_add_co_u32_e32 v66, vcc, s6, v44
	v_ashrrev_i32_e32 v179, 31, v178
	v_lshl_add_u64 v[78:79], v[44:45], 0, s[8:9]
	v_addc_co_u32_e32 v67, vcc, 0, v45, vcc
	v_lshlrev_b64 v[44:45], 12, v[178:179]
	global_load_dwordx4 v[2:5], v0, s[0:1] offset:48
	global_load_dwordx4 v[6:9], v0, s[0:1] offset:32
	global_load_dwordx4 v[10:13], v0, s[0:1] offset:16
	global_load_dwordx4 v[14:17], v0, s[0:1]
	global_load_dwordx4 v[18:21], v0, s[0:1] offset:112
	global_load_dwordx4 v[22:25], v0, s[0:1] offset:96
	global_load_dwordx4 v[26:29], v0, s[0:1] offset:80
	global_load_dwordx4 v[30:33], v0, s[0:1] offset:64
	v_or_b32_e32 v94, 0x2000, v0
	v_or_b32_e32 v110, 0x4000, v0
	v_or_b32_e32 v126, 0x6000, v0
	v_lshl_add_u64 v[44:45], s[4:5], 0, v[44:45]
	v_lshlrev_b32_e32 v0, 4, v43
	v_lshl_add_u64 v[82:83], v[44:45], 0, v[0:1]
	v_and_b32_e32 v44, 64, v203
	v_add_u32_e32 v44, 64, v44
	v_xor_b32_e32 v45, 1, v203
	v_cmp_lt_i32_e32 vcc, v45, v44
	v_readlane_b32 s6, v250, 4
	v_lshlrev_b64 v[172:173], 11, v[178:179]
	v_cndmask_b32_e32 v45, v203, v45, vcc
	v_lshlrev_b32_e32 v163, 2, v45
	v_xor_b32_e32 v45, 2, v203
	v_cmp_lt_i32_e32 vcc, v45, v44
	v_add_u32_e32 v42, s6, v42
	v_and_b32_e32 v220, 15, v43
	v_lshrrev_b32_e32 v221, 1, v43
	v_and_b32_e32 v221, 24, v221
	v_or_b32_e32 v221, 0x200000, v221
	v_cmp_eq_u32_e64 s[40:41], 0, v220
	v_cndmask_b32_e32 v45, v203, v45, vcc
	v_lshlrev_b32_e32 v180, 2, v45
	v_xor_b32_e32 v45, 4, v203
	v_cmp_lt_i32_e32 vcc, v45, v44
	v_lshl_or_b32 v172, v43, 3, v172
	v_ashrrev_i32_e32 v43, 31, v42
	v_cndmask_b32_e32 v45, v203, v45, vcc
	v_lshlrev_b32_e32 v181, 2, v45
	v_xor_b32_e32 v45, 8, v203
	v_cmp_lt_i32_e32 vcc, v45, v44
	v_lshlrev_b64 v[42:43], 12, v[42:43]
	v_or_b32_e32 v42, v42, v0
	v_cndmask_b32_e32 v45, v203, v45, vcc
	v_lshlrev_b32_e32 v182, 2, v45
	v_xor_b32_e32 v45, 16, v203
	v_cmp_lt_i32_e32 vcc, v45, v44
	global_load_dwordx4 v[34:37], v[34:35], off offset:64
	s_nop 0
	global_load_dwordx4 v[38:41], v[46:47], off offset:48
	v_cndmask_b32_e32 v45, v203, v45, vcc
	v_lshlrev_b32_e32 v183, 2, v45
	v_xor_b32_e32 v45, 32, v203
	v_cmp_lt_i32_e32 vcc, v45, v44
	v_lshl_add_u64 v[174:175], s[4:5], 0, v[42:43]
	v_add_u32_e32 v185, 0, v0
	v_cndmask_b32_e32 v44, v203, v45, vcc
	v_lshlrev_b32_e32 v184, 2, v44
	global_load_dwordx4 v[42:45], v[46:47], off offset:32
	s_nop 0
	global_load_dwordx4 v[46:49], v[46:47], off offset:16
	s_nop 0
	global_load_dwordx4 v[50:53], v[50:51], off offset:64
	s_nop 0
	global_load_dwordx4 v[54:57], v[62:63], off offset:48
	global_load_dwordx4 v[58:61], v[62:63], off offset:32
	s_nop 0
	global_load_dwordx4 v[62:65], v[62:63], off offset:16
	s_nop 0
	global_load_dwordx4 v[66:69], v[66:67], off offset:64
	s_nop 0
	global_load_dwordx4 v[70:73], v[78:79], off offset:48
	global_load_dwordx4 v[74:77], v[78:79], off offset:32
	s_nop 0
	global_load_dwordx4 v[78:81], v[78:79], off offset:16
	s_nop 0
	global_load_dwordx4 v[158:161], v[82:83], off
	global_load_dwordx4 v[154:157], v[82:83], off offset:1024
	global_load_dwordx4 v[150:153], v[82:83], off offset:2048
	global_load_dwordx4 v[146:149], v[82:83], off offset:3072
	s_nop 0
	global_load_dwordx4 v[82:85], v94, s[0:1] offset:48
	global_load_dwordx4 v[86:89], v94, s[0:1] offset:32
	global_load_dwordx4 v[90:93], v94, s[0:1] offset:16
	s_nop 0
	global_load_dwordx4 v[94:97], v94, s[0:1]
	s_nop 0
	global_load_dwordx4 v[98:101], v110, s[0:1] offset:48
	global_load_dwordx4 v[102:105], v110, s[0:1] offset:32
	global_load_dwordx4 v[106:109], v110, s[0:1] offset:16
	s_nop 0
	global_load_dwordx4 v[110:113], v110, s[0:1]
	s_nop 0
	global_load_dwordx4 v[114:117], v126, s[0:1] offset:48
	global_load_dwordx4 v[118:121], v126, s[0:1] offset:32
	global_load_dwordx4 v[122:125], v126, s[0:1] offset:16
	s_nop 0
	global_load_dwordx4 v[126:129], v126, s[0:1]
	s_mov_b64 s[48:49], 0
	v_lshlrev_b64 v[176:177], 5, v[178:179]
	s_branch .LBB0_140
.LBB0_139:
	s_or_b64 exec, exec, s[0:1]
	s_and_b64 s[0:1], exec, s[42:43]
	s_or_b64 s[48:49], s[0:1], s[48:49]
	v_readlane_b32 s0, v250, 15
	v_readlane_b32 s1, v250, 16
	v_mov_b32_e32 v178, v179

; DI void phase_norm(const Params& p, int l, const float* xin, LAS unsigned char* lds, int G, int bid) {
;     ...
;     for (int row = gw; row < M; row += NGW) {
;         const int b = row / S;
;         f32x4 v[4]; float ss = 0.f;
; #pragma unroll
;         for (int j = 0; j < 4; ++j) v[j] = vn[j];
;         if (row + NGW < M) {
; #pragma unroll
;             for (int j = 0; j < 4; ++j) vn[j] = ((const f32x4*)(xin + (size_t)(row + NGW) * D) + lane)[64 * j]; }
	v_mov_b32_e32 v158, v130
	v_lshl_add_u64 v[176:177], v[176:177], 0, s[0:1]
	v_readlane_b32 s0, v250, 17
	v_readlane_b32 s1, v250, 18

; DI void phase_norm(const Params& p, int l, const float* xin, LAS unsigned char* lds, int G, int bid) {
;     ...
;     for (int row = gw; row < M; row += NGW) {
;         const int b = row / S;
;         f32x4 v[4]; float ss = 0.f;
; #pragma unroll
;         for (int j = 0; j < 4; ++j) v[j] = vn[j];
;         if (row + NGW < M) {
; #pragma unroll
;             for (int j = 0; j < 4; ++j) vn[j] = ((const f32x4*)(xin + (size_t)(row + NGW) * D) + lane)[64 * j]; }
	v_mov_b32_e32 v159, v131

; DI void phase_norm(const Params& p, int l, const float* xin, LAS unsigned char* lds, int G, int bid) {
;     ...
;     for (int row = gw; row < M; row += NGW) {
;         const int b = row / S;
;         f32x4 v[4]; float ss = 0.f;
; #pragma unroll
;         for (int j = 0; j < 4; ++j) v[j] = vn[j];
;         if (row + NGW < M) {
; #pragma unroll
;             for (int j = 0; j < 4; ++j) vn[j] = ((const f32x4*)(xin + (size_t)(row + NGW) * D) + lane)[64 * j]; }
	v_mov_b32_e32 v160, v132
	v_lshl_add_u64 v[172:173], v[172:173], 0, s[0:1]
	v_readlane_b32 s0, v250, 19
	v_readlane_b32 s1, v250, 20

; DI void phase_norm(const Params& p, int l, const float* xin, LAS unsigned char* lds, int G, int bid) {
;     ...
;     for (int row = gw; row < M; row += NGW) {
;         const int b = row / S;
;         f32x4 v[4]; float ss = 0.f;
; #pragma unroll
;         for (int j = 0; j < 4; ++j) v[j] = vn[j];
;         if (row + NGW < M) {
; #pragma unroll
;             for (int j = 0; j < 4; ++j) vn[j] = ((const f32x4*)(xin + (size_t)(row + NGW) * D) + lane)[64 * j]; }
	v_mov_b32_e32 v161, v133
	v_mov_b32_e32 v154, v134
	v_lshl_add_u64 v[174:175], v[174:175], 0, s[0:1]
	v_mov_b32_e32 v155, v135
	v_mov_b32_e32 v156, v136
	v_mov_b32_e32 v157, v137
	v_mov_b32_e32 v150, v138
	v_mov_b32_e32 v151, v139
	v_mov_b32_e32 v152, v140
	v_mov_b32_e32 v153, v141
	v_mov_b32_e32 v146, v142
	v_mov_b32_e32 v147, v143
	v_mov_b32_e32 v148, v144
	v_mov_b32_e32 v149, v145
	s_andn2_b64 exec, exec, s[48:49]
	s_cbranch_execz .LBB0_144

; #define LAS __attribute__((address_space(3)))
; DI void phase_norm(const Params& p, int l, const float* xin, LAS unsigned char* lds, int G, int bid) {
;     ...
;         for (int j = 0; j < 4; ++j) ss += (v[j].x * v[j].x + v[j].y * v[j].y) + (v[j].z * v[j].z + v[j].w * v[j].w);
;         const float rstd = 1.0f / sqrtf(wave_sum(ss) * (1.f / D) + EPS);
;         f32x4 g0 = {0.f, 0.f, 0.f, 0.f}, g1 = {0.f, 0.f, 0.f, 0.f};
;         unsigned long long* o8 = (unsigned long long*)(H + (size_t)row * D) + lane;
; #pragma unroll
;         for (int j = 0; j < 4; ++j) {
;             const int k = 256 * j + 4 * lane;
;             const f32x4 aa = *(const LAS f32x4*)(pa + b * 1024 + k), sh = *(const LAS f32x4*)(pb + b * 1024 + k);
;             const f32x4 h = (v[j] * rstd) * aa + sh;
.LBB0_142:
	s_or_b64 exec, exec, s[0:1]
	v_ashrrev_i32_e32 v0, 31, v178
	v_lshrrev_b32_e32 v0, 19, v0
	v_add_u32_e32 v0, v178, v0
	v_pk_mul_f32 v[186:187], v[154:155], v[154:155]
	v_pk_mul_f32 v[188:189], v[156:157], v[156:157]
	v_pk_mul_f32 v[190:191], v[158:159], v[158:159]
	v_pk_mul_f32 v[192:193], v[160:161], v[160:161]
	v_ashrrev_i32_e32 v178, 13, v0
	v_mov_b32_e32 v194, v190
	v_mov_b32_e32 v195, v193
	v_pk_mov_b32 v[190:191], v[190:191], v[192:193] op_sel:[1,0]
	v_mov_b32_e32 v192, v186
	v_mov_b32_e32 v193, v189
	v_pk_mov_b32 v[186:187], v[186:187], v[188:189] op_sel:[1,0]
	v_mul_f32_e32 v0, v150, v150
	v_pk_add_f32 v[190:191], v[190:191], v[194:195]
	v_pk_add_f32 v[186:187], v[186:187], v[192:193]
	v_pk_fma_f32 v[188:189], v[150:151], v[150:151], v[0:1] op_sel_hi:[1,1,0]
	v_mul_f32_e32 v0, v152, v152
	v_pk_add_f32 v[190:191], v[190:191], v[190:191] op_sel_hi:[0,1]
	v_pk_add_f32 v[186:187], v[186:187], v[186:187] op_sel_hi:[0,1]
	v_pk_fma_f32 v[192:193], v[152:153], v[152:153], v[0:1] op_sel_hi:[1,1,0]
	v_mul_f32_e32 v188, v146, v146
	v_mul_f32_e32 v192, v147, v147
	v_mul_f32_e32 v190, v148, v148
	v_mul_f32_e32 v186, v149, v149
	v_pk_add_f32 v[188:189], v[188:189], v[192:193]
	v_pk_add_f32 v[186:187], v[190:191], v[186:187]
	s_mov_b32 s0, 0xf800000
	v_pk_add_f32 v[186:187], v[188:189], v[186:187]
	v_lshl_add_u32 v178, v178, 12, v185
	v_add_f32_e32 v0, v186, v187
	v_lshl_add_u64 v[194:195], s[92:93], 0, v[172:173]
	s_nop 1
	v_add_f32_dpp v0, v0, v0 quad_perm:[1,0,3,2] row_mask:0xf bank_mask:0xf
	s_nop 1
	v_add_f32_dpp v0, v0, v0 quad_perm:[2,3,0,1] row_mask:0xf bank_mask:0xf
	s_nop 1
	v_add_f32_dpp v0, v0, v0 row_half_mirror row_mask:0xf bank_mask:0xf
	s_nop 1
	v_add_f32_dpp v0, v0, v0 row_mirror row_mask:0xf bank_mask:0xf
	s_nop 3
	v_readlane_b32 s17, v0, 0
	v_readlane_b32 s23, v0, 16
	v_readlane_b32 s28, v0, 32
	v_readlane_b32 s29, v0, 48
	s_nop 1
	v_mov_b32_e32 v0, s17
	v_mov_b32_e32 v186, s28
	v_add_f32_e32 v0, s23, v0
	v_add_f32_e32 v186, s29, v186
	v_add_f32_e32 v0, v0, v186
	v_fmamk_f32 v0, v0, 0x3a800000, v204
	v_cmp_gt_f32_e32 vcc, s0, v0
	v_mul_f32_e32 v186, 0x4f800000, v0
	s_nop 0
	v_cndmask_b32_e32 v0, v0, v186, vcc
	v_sqrt_f32_e32 v186, v0
	s_nop 0
	v_add_u32_e32 v187, -1, v186
	v_fma_f32 v188, -v187, v186, v0
	v_cmp_ge_f32_e64 s[0:1], 0, v188
	v_add_u32_e32 v188, 1, v186
	s_nop 0
	v_cndmask_b32_e64 v187, v186, v187, s[0:1]
	v_fma_f32 v186, -v188, v186, v0
	v_cmp_lt_f32_e64 s[0:1], 0, v186
	s_nop 1
	v_cndmask_b32_e64 v186, v187, v188, s[0:1]
	v_mul_f32_e32 v187, 0x37800000, v186
	v_cndmask_b32_e32 v186, v186, v187, vcc
	v_cmp_class_f32_e32 vcc, v0, v205
	s_nop 1
	v_cndmask_b32_e32 v0, v186, v0, vcc
	v_div_scale_f32 v186, s[0:1], v0, v0, 1.0
	v_rcp_f32_e32 v187, v186
	s_brev_b32 s0, 32
	v_fma_f32 v188, -v186, v187, 1.0
	v_fmac_f32_e32 v187, v188, v187
	v_div_scale_f32 v188, vcc, 1.0, v0, 1.0
	v_mul_f32_e32 v189, v188, v187
	v_fma_f32 v190, -v186, v189, v188
	v_fmac_f32_e32 v189, v190, v187
	v_fma_f32 v186, -v186, v189, v188
	v_div_fmas_f32 v186, v186, v187, v189
	v_div_fixup_f32 v0, v186, v0, 1.0
	ds_read_b128 v[186:189], v178
	ds_read_b128 v[190:193], v178 offset:16384
	v_pk_mul_f32 v[158:159], v[158:159], v[0:1] op_sel_hi:[1,0]
	v_pk_mul_f32 v[160:161], v[160:161], v[0:1] op_sel_hi:[1,0]
	v_pk_mul_f32 v[154:155], v[154:155], v[0:1] op_sel_hi:[1,0]
	v_pk_mul_f32 v[156:157], v[156:157], v[0:1] op_sel_hi:[1,0]
	s_waitcnt lgkmcnt(0)
	v_pk_fma_f32 v[158:159], v[186:187], v[158:159], v[190:191]
	v_pk_fma_f32 v[160:161], v[188:189], v[160:161], v[192:193]
	v_pk_fma_f32 v[186:187], v[14:15], v[158:159], 0 op_sel_hi:[1,0,0]
	v_pk_fma_f32 v[188:189], v[16:17], v[158:159], 0 op_sel_hi:[1,0,0]
	v_pk_fma_f32 v[186:187], v[6:7], v[158:159], v[186:187] op_sel:[0,1,0]
	v_pk_fma_f32 v[190:191], v[10:11], v[158:159], 0 op_sel_hi:[1,0,0]
	v_pk_fma_f32 v[192:193], v[12:13], v[158:159], 0 op_sel_hi:[1,0,0]
	v_pk_fma_f32 v[186:187], v[30:31], v[160:161], v[186:187] op_sel_hi:[1,0,1]
	v_pk_fma_f32 v[188:189], v[8:9], v[158:159], v[188:189] op_sel:[0,1,0]
	v_pk_fma_f32 v[192:193], v[4:5], v[158:159], v[192:193] op_sel:[0,1,0]
	v_pk_fma_f32 v[190:191], v[2:3], v[158:159], v[190:191] op_sel:[0,1,0]
	v_pk_fma_f32 v[198:199], v[22:23], v[160:161], v[186:187] op_sel:[0,1,0]
	v_cvt_pk_bf16_f32 v186, v158, v159
	v_add_co_u32_e32 v158, vcc, s0, v194
	v_cvt_pk_bf16_f32 v187, v160, v161
	s_nop 0
	v_addc_co_u32_e32 v159, vcc, 0, v195, vcc
	v_pk_fma_f32 v[188:189], v[32:33], v[160:161], v[188:189] op_sel_hi:[1,0,1]
	v_pk_fma_f32 v[190:191], v[26:27], v[160:161], v[190:191] op_sel_hi:[1,0,1]
	v_pk_fma_f32 v[192:193], v[28:29], v[160:161], v[192:193] op_sel_hi:[1,0,1]
	global_store_dwordx2 v[158:159], v[186:187], off
	v_pk_fma_f32 v[196:197], v[24:25], v[160:161], v[188:189] op_sel:[0,1,0]
	v_pk_fma_f32 v[200:201], v[20:21], v[160:161], v[192:193] op_sel:[0,1,0]
	v_pk_fma_f32 v[218:219], v[18:19], v[160:161], v[190:191] op_sel:[0,1,0]
	ds_read_b128 v[186:189], v178 offset:1024
	ds_read_b128 v[190:193], v178 offset:17408
	v_pk_mul_f32 v[150:151], v[150:151], v[0:1] op_sel_hi:[1,0]
	v_pk_mul_f32 v[152:153], v[152:153], v[0:1] op_sel_hi:[1,0]
	v_pk_mul_f32 v[146:147], v[146:147], v[0:1] op_sel_hi:[1,0]
	v_pk_mul_f32 v[148:149], v[148:149], v[0:1] op_sel_hi:[1,0]
	s_waitcnt lgkmcnt(0)
	v_pk_fma_f32 v[154:155], v[186:187], v[154:155], v[190:191]
	v_pk_fma_f32 v[156:157], v[188:189], v[156:157], v[192:193]
	s_waitcnt vmcnt(9)
; #define LAS __attribute__((address_space(3)))
; DI void phase_norm(const Params& p, int l, const float* xin, LAS unsigned char* lds, int G, int bid) {
;     ...
; #pragma unroll
;         for (int j = 0; j < 4; ++j) {
;             const int k = 256 * j + 4 * lane;
;             const f32x4 aa = *(const LAS f32x4*)(pa + b * 1024 + k), sh = *(const LAS f32x4*)(pb + b * 1024 + k);
;             const f32x4 h = (v[j] * rstd) * aa + sh;
; #pragma unroll
;             for (int e = 0; e < 4; ++e) { g0 += w0[j][e] * h[e]; g1 += w1[j][e] * h[e]; }
;             o8[64 * j] = (unsigned long long)cvt_pk_bf16(h.x, h.y) | ((unsigned long long)cvt_pk_bf16(h.z, h.w) << 32);
;         }
; #pragma unroll
;         for (int e = 0; e < 4; ++e) { g0[e] = wave_sum(g0[e]); g1[e] = wave_sum(g1[e]); }
;         if (lane == 0) { *(f32x4*)(gates + (size_t)row * 8) = g0; *(f32x4*)(gates + (size_t)row * 8 + 4) = g1; }
	v_pk_fma_f32 v[160:161], v[94:95], v[154:155], v[198:199] op_sel_hi:[1,0,1]
	v_pk_fma_f32 v[186:187], v[96:97], v[154:155], v[196:197] op_sel_hi:[1,0,1]
	v_pk_fma_f32 v[188:189], v[90:91], v[154:155], v[218:219] op_sel_hi:[1,0,1]
	v_pk_fma_f32 v[190:191], v[92:93], v[154:155], v[200:201] op_sel_hi:[1,0,1]
	v_pk_fma_f32 v[186:187], v[88:89], v[154:155], v[186:187] op_sel:[0,1,0]
	v_pk_fma_f32 v[160:161], v[86:87], v[154:155], v[160:161] op_sel:[0,1,0]
	v_pk_fma_f32 v[190:191], v[84:85], v[154:155], v[190:191] op_sel:[0,1,0]
	v_pk_fma_f32 v[188:189], v[82:83], v[154:155], v[188:189] op_sel:[0,1,0]
	v_cvt_pk_bf16_f32 v154, v154, v155
	v_cvt_pk_bf16_f32 v155, v156, v157
	v_pk_fma_f32 v[160:161], v[34:35], v[156:157], v[160:161] op_sel_hi:[1,0,1]
	v_pk_fma_f32 v[186:187], v[36:37], v[156:157], v[186:187] op_sel_hi:[1,0,1]
	v_pk_fma_f32 v[188:189], v[46:47], v[156:157], v[188:189] op_sel_hi:[1,0,1]
	v_pk_fma_f32 v[190:191], v[48:49], v[156:157], v[190:191] op_sel_hi:[1,0,1]
	global_store_dwordx2 v[158:159], v[154:155], off offset:512
	v_pk_fma_f32 v[192:193], v[44:45], v[156:157], v[186:187] op_sel:[0,1,0]
	v_pk_fma_f32 v[160:161], v[42:43], v[156:157], v[160:161] op_sel:[0,1,0]
	v_pk_fma_f32 v[190:191], v[40:41], v[156:157], v[190:191] op_sel:[0,1,0]
	v_pk_fma_f32 v[194:195], v[38:39], v[156:157], v[188:189] op_sel:[0,1,0]
	ds_read_b128 v[154:157], v178 offset:2048
	ds_read_b128 v[186:189], v178 offset:18432
	s_waitcnt lgkmcnt(0)
	v_pk_fma_f32 v[150:151], v[154:155], v[150:151], v[186:187]
	v_pk_fma_f32 v[152:153], v[156:157], v[152:153], v[188:189]
	s_waitcnt vmcnt(6)
	v_pk_fma_f32 v[154:155], v[110:111], v[150:151], v[160:161] op_sel_hi:[1,0,1]
	v_pk_fma_f32 v[156:157], v[112:113], v[150:151], v[192:193] op_sel_hi:[1,0,1]
	v_pk_fma_f32 v[160:161], v[106:107], v[150:151], v[194:195] op_sel_hi:[1,0,1]
	v_pk_fma_f32 v[186:187], v[108:109], v[150:151], v[190:191] op_sel_hi:[1,0,1]
	v_pk_fma_f32 v[156:157], v[104:105], v[150:151], v[156:157] op_sel:[0,1,0]
	v_pk_fma_f32 v[154:155], v[102:103], v[150:151], v[154:155] op_sel:[0,1,0]
	v_pk_fma_f32 v[186:187], v[100:101], v[150:151], v[186:187] op_sel:[0,1,0]
	v_pk_fma_f32 v[160:161], v[98:99], v[150:151], v[160:161] op_sel:[0,1,0]
	v_cvt_pk_bf16_f32 v150, v150, v151
	v_cvt_pk_bf16_f32 v151, v152, v153
	v_pk_fma_f32 v[154:155], v[50:51], v[152:153], v[154:155] op_sel_hi:[1,0,1]
	v_pk_fma_f32 v[156:157], v[52:53], v[152:153], v[156:157] op_sel_hi:[1,0,1]
	v_pk_fma_f32 v[160:161], v[62:63], v[152:153], v[160:161] op_sel_hi:[1,0,1]
	v_pk_fma_f32 v[186:187], v[64:65], v[152:153], v[186:187] op_sel_hi:[1,0,1]
	global_store_dwordx2 v[158:159], v[150:151], off offset:1024
	v_pk_fma_f32 v[188:189], v[60:61], v[152:153], v[156:157] op_sel:[0,1,0]
	v_pk_fma_f32 v[190:191], v[58:59], v[152:153], v[154:155] op_sel:[0,1,0]
	v_pk_fma_f32 v[186:187], v[56:57], v[152:153], v[186:187] op_sel:[0,1,0]
	v_pk_fma_f32 v[160:161], v[54:55], v[152:153], v[160:161] op_sel:[0,1,0]
	ds_read_b128 v[150:153], v178 offset:3072
	ds_read_b128 v[154:157], v178 offset:19456
	s_waitcnt lgkmcnt(0)
	v_pk_fma_f32 v[146:147], v[146:147], v[150:151], v[154:155]
	s_waitcnt vmcnt(3)
	v_pk_fma_f32 v[150:151], v[126:127], v[146:147], v[190:191] op_sel_hi:[1,0,1]
	v_pk_fma_f32 v[148:149], v[148:149], v[152:153], v[156:157]
	v_pk_fma_f32 v[150:151], v[118:119], v[146:147], v[150:151] op_sel:[0,1,0]
	v_pk_fma_f32 v[152:153], v[128:129], v[146:147], v[188:189] op_sel_hi:[1,0,1]
	v_pk_fma_f32 v[154:155], v[122:123], v[146:147], v[160:161] op_sel_hi:[1,0,1]
	v_pk_fma_f32 v[156:157], v[124:125], v[146:147], v[186:187] op_sel_hi:[1,0,1]
	v_pk_fma_f32 v[150:151], v[66:67], v[148:149], v[150:151] op_sel_hi:[1,0,1]
	v_pk_fma_f32 v[152:153], v[120:121], v[146:147], v[152:153] op_sel:[0,1,0]
	v_pk_fma_f32 v[156:157], v[116:117], v[146:147], v[156:157] op_sel:[0,1,0]
	v_pk_fma_f32 v[154:155], v[114:115], v[146:147], v[154:155] op_sel:[0,1,0]
	v_pk_fma_f32 v[160:161], v[74:75], v[148:149], v[150:151] op_sel:[0,1,0]
	v_cvt_pk_bf16_f32 v146, v146, v147
	v_cvt_pk_bf16_f32 v147, v148, v149
	global_store_dwordx2 v[158:159], v[146:147], off offset:1536
	v_pk_fma_f32 v[152:153], v[68:69], v[148:149], v[152:153] op_sel_hi:[1,0,1]
	v_pk_fma_f32 v[154:155], v[78:79], v[148:149], v[154:155] op_sel_hi:[1,0,1]
	v_pk_fma_f32 v[156:157], v[80:81], v[148:149], v[156:157] op_sel_hi:[1,0,1]
	v_pk_fma_f32 v[152:153], v[76:77], v[148:149], v[152:153] op_sel:[0,1,0]
	v_pk_fma_f32 v[150:151], v[72:73], v[148:149], v[156:157] op_sel:[0,1,0]
	v_pk_fma_f32 v[154:155], v[70:71], v[148:149], v[154:155] op_sel:[0,1,0]
	s_nop 1
	v_permlane32_swap_b32 v160, v154
	v_permlane32_swap_b32 v161, v155
	v_permlane32_swap_b32 v152, v150
	v_permlane32_swap_b32 v153, v151
	v_pk_add_f32 v[160:161], v[160:161], v[154:155]
	v_pk_add_f32 v[152:153], v[152:153], v[150:151]
	s_nop 1
	v_permlane16_swap_b32 v160, v152
	v_permlane16_swap_b32 v161, v153
	v_pk_add_f32 v[160:161], v[160:161], v[152:153]
	v_add_u32_e32 v146, v176, v221
	s_nop 0
	v_add_f32_dpp v160, v160, v160 quad_perm:[1,0,3,2] row_mask:0xf bank_mask:0xf
	v_add_f32_dpp v161, v161, v161 quad_perm:[1,0,3,2] row_mask:0xf bank_mask:0xf
	s_nop 0
	v_add_f32_dpp v160, v160, v160 quad_perm:[2,3,0,1] row_mask:0xf bank_mask:0xf
	v_add_f32_dpp v161, v161, v161 quad_perm:[2,3,0,1] row_mask:0xf bank_mask:0xf
	s_nop 0
	v_add_f32_dpp v160, v160, v160 row_half_mirror row_mask:0xf bank_mask:0xf
	v_add_f32_dpp v161, v161, v161 row_half_mirror row_mask:0xf bank_mask:0xf
	s_nop 0
	v_add_f32_dpp v160, v160, v160 row_mirror row_mask:0xf bank_mask:0xf
	v_add_f32_dpp v161, v161, v161 row_mirror row_mask:0xf bank_mask:0xf
	s_and_saveexec_b64 s[0:1], s[40:41]
	global_store_dwordx2 v146, v[160:161], s[92:93]
	s_branch .LBB0_139
